# LDS-DMA loops: the next stage's DMA loads spread over the first MFMAs of a stage (an MFMA in each M0-write to load gap) instead of issued at the stage top
# speedup vs baseline: 1.0075x; 1.0075x over previous
.Lf2_stage0:
	ds_read_b128 v[66:69], v130 offset:0
	ds_read_b128 v[74:77], v134 offset:16384
	ds_read_b128 v[78:81], v134 offset:20480
	ds_read_b128 v[70:73], v130 offset:4096
	ds_read_b128 v[82:85], v131 offset:0
	ds_read_b128 v[90:93], v135 offset:16384
	ds_read_b128 v[94:97], v135 offset:20480
	ds_read_b128 v[86:89], v131 offset:4096
	ds_read_b128 v[98:101], v132 offset:0
	ds_read_b128 v[106:109], v136 offset:16384
	ds_read_b128 v[110:113], v136 offset:20480
	ds_read_b128 v[102:105], v132 offset:4096
	s_cmp_ge_u32 s22, 43
	s_cbranch_scc1 .Lf2_nl0
	s_waitcnt lgkmcnt(10)
	s_add_u32 m0, s38, 0x8000
	v_mfma_f32_32x32x16_f16 v[50:65], v[66:69], v[74:77], v[50:65]
	global_load_lds_dwordx4 v152, s[10:11]
	s_waitcnt lgkmcnt(9)
	s_add_u32 m0, s38, 0xc000
	v_mfma_f32_32x32x16_f16 v[34:49], v[66:69], v[78:81], v[34:49]
	global_load_lds_dwordx4 v152, s[8:9]
	s_waitcnt lgkmcnt(8)
	s_add_u32 m0, s38, 0x9000
	v_mfma_f32_32x32x16_f16 v[18:33], v[70:73], v[74:77], v[18:33]
	global_load_lds_dwordx4 v150, s[10:11]
	s_add_u32 m0, s38, 0xd000
	v_mfma_f32_32x32x16_f16 v[2:17], v[70:73], v[78:81], v[2:17]
	global_load_lds_dwordx4 v150, s[8:9]
	ds_read_b128 v[114:117], v133 offset:0
	ds_read_b128 v[122:125], v137 offset:16384
	ds_read_b128 v[126:129], v137 offset:20480
	ds_read_b128 v[118:121], v133 offset:4096
	s_waitcnt lgkmcnt(10)
	s_add_u32 m0, s38, 0xa000
	v_mfma_f32_32x32x16_f16 v[50:65], v[82:85], v[90:93], v[50:65]
	global_load_lds_dwordx4 v148, s[10:11]
	s_waitcnt lgkmcnt(9)
	s_add_u32 m0, s38, 0xe000
	v_mfma_f32_32x32x16_f16 v[34:49], v[82:85], v[94:97], v[34:49]
	global_load_lds_dwordx4 v148, s[8:9]
	s_waitcnt lgkmcnt(8)
	s_add_u32 m0, s38, 0xb000
	v_mfma_f32_32x32x16_f16 v[18:33], v[86:89], v[90:93], v[18:33]
	global_load_lds_dwordx4 v146, s[10:11]
	s_add_u32 m0, s38, 0xf000
	v_mfma_f32_32x32x16_f16 v[2:17], v[86:89], v[94:97], v[2:17]
	global_load_lds_dwordx4 v146, s[8:9]
	s_add_u32 s8, s8, 0x80
	s_addc_u32 s9, s9, 0
	s_add_u32 s10, s10, 0x80
	s_addc_u32 s11, s11, 0
	s_branch .Lf2_dd0

.Lf2_dd0:
	s_waitcnt lgkmcnt(6)
	v_mfma_f32_32x32x16_f16 v[50:65], v[98:101], v[106:109], v[50:65]
	s_waitcnt lgkmcnt(5)
	v_mfma_f32_32x32x16_f16 v[34:49], v[98:101], v[110:113], v[34:49]
	s_waitcnt lgkmcnt(4)
	v_mfma_f32_32x32x16_f16 v[18:33], v[102:105], v[106:109], v[18:33]
	v_mfma_f32_32x32x16_f16 v[2:17], v[102:105], v[110:113], v[2:17]
	s_waitcnt lgkmcnt(2)
	v_mfma_f32_32x32x16_f16 v[50:65], v[114:117], v[122:125], v[50:65]
	s_waitcnt lgkmcnt(1)
	v_mfma_f32_32x32x16_f16 v[34:49], v[114:117], v[126:129], v[34:49]
	s_waitcnt lgkmcnt(0)
	v_mfma_f32_32x32x16_f16 v[18:33], v[118:121], v[122:125], v[18:33]
	v_mfma_f32_32x32x16_f16 v[2:17], v[118:121], v[126:129], v[2:17]
	s_add_i32 s22, s22, 1
	s_waitcnt vmcnt(0)
	s_barrier
.Lf2_stage1:
	ds_read_b128 v[66:69], v130 offset:32768
	ds_read_b128 v[74:77], v134 offset:49152
	ds_read_b128 v[78:81], v134 offset:53248
	ds_read_b128 v[70:73], v130 offset:36864
	ds_read_b128 v[82:85], v131 offset:32768
	ds_read_b128 v[90:93], v135 offset:49152
	ds_read_b128 v[94:97], v135 offset:53248
	ds_read_b128 v[86:89], v131 offset:36864
	ds_read_b128 v[98:101], v132 offset:32768
	ds_read_b128 v[106:109], v136 offset:49152
	ds_read_b128 v[110:113], v136 offset:53248
	ds_read_b128 v[102:105], v132 offset:36864
	s_cmp_ge_u32 s22, 43
	s_cbranch_scc1 .Lf2_nl1
	s_waitcnt lgkmcnt(10)
	s_add_u32 m0, s38, 0x0
	v_mfma_f32_32x32x16_f16 v[50:65], v[66:69], v[74:77], v[50:65]
	global_load_lds_dwordx4 v152, s[10:11]
	s_waitcnt lgkmcnt(9)
	s_add_u32 m0, s38, 0x4000
	v_mfma_f32_32x32x16_f16 v[34:49], v[66:69], v[78:81], v[34:49]
	global_load_lds_dwordx4 v152, s[8:9]
	s_waitcnt lgkmcnt(8)
	s_add_u32 m0, s38, 0x1000
	v_mfma_f32_32x32x16_f16 v[18:33], v[70:73], v[74:77], v[18:33]
	global_load_lds_dwordx4 v150, s[10:11]
	s_add_u32 m0, s38, 0x5000
	v_mfma_f32_32x32x16_f16 v[2:17], v[70:73], v[78:81], v[2:17]
	global_load_lds_dwordx4 v150, s[8:9]
	ds_read_b128 v[114:117], v133 offset:32768
	ds_read_b128 v[122:125], v137 offset:49152
	ds_read_b128 v[126:129], v137 offset:53248
	ds_read_b128 v[118:121], v133 offset:36864
	s_waitcnt lgkmcnt(10)
	s_add_u32 m0, s38, 0x2000
	v_mfma_f32_32x32x16_f16 v[50:65], v[82:85], v[90:93], v[50:65]
	global_load_lds_dwordx4 v148, s[10:11]
	s_waitcnt lgkmcnt(9)
	s_add_u32 m0, s38, 0x6000
	v_mfma_f32_32x32x16_f16 v[34:49], v[82:85], v[94:97], v[34:49]
	global_load_lds_dwordx4 v148, s[8:9]
	s_waitcnt lgkmcnt(8)
	s_add_u32 m0, s38, 0x3000
	v_mfma_f32_32x32x16_f16 v[18:33], v[86:89], v[90:93], v[18:33]
	global_load_lds_dwordx4 v146, s[10:11]
	s_add_u32 m0, s38, 0x7000
	v_mfma_f32_32x32x16_f16 v[2:17], v[86:89], v[94:97], v[2:17]
	global_load_lds_dwordx4 v146, s[8:9]
	s_add_u32 s8, s8, 0x80
	s_addc_u32 s9, s9, 0
	s_add_u32 s10, s10, 0x80
	s_addc_u32 s11, s11, 0
	s_branch .Lf2_dd1

; DI void gemm_tile_deep(const h16* __restrict__ A, int lda, const h16* __restrict__ B, int ldb, int K, f32x16 (&acc)[2][2], h16* sm) {
;     ...
;   for (int kt = 0; kt < nk; kt += 2) {
;     DEEP_HALF(ra0, rb0, 0, kt)
;     DEEP_HALF(ra1, rb1, 1, kt + 1)
;   }
.Lf2_dd1:
	s_waitcnt lgkmcnt(6)
	v_mfma_f32_32x32x16_f16 v[50:65], v[98:101], v[106:109], v[50:65]
	s_waitcnt lgkmcnt(5)
	v_mfma_f32_32x32x16_f16 v[34:49], v[98:101], v[110:113], v[34:49]
	s_waitcnt lgkmcnt(4)
	v_mfma_f32_32x32x16_f16 v[18:33], v[102:105], v[106:109], v[18:33]
	v_mfma_f32_32x32x16_f16 v[2:17], v[102:105], v[110:113], v[2:17]
	s_waitcnt lgkmcnt(2)
	v_mfma_f32_32x32x16_f16 v[50:65], v[114:117], v[122:125], v[50:65]
	s_waitcnt lgkmcnt(1)
	v_mfma_f32_32x32x16_f16 v[34:49], v[114:117], v[126:129], v[34:49]
	s_waitcnt lgkmcnt(0)
	v_mfma_f32_32x32x16_f16 v[18:33], v[118:121], v[122:125], v[18:33]
	v_mfma_f32_32x32x16_f16 v[2:17], v[118:121], v[126:129], v[2:17]
	s_add_i32 s22, s22, 1
	s_cmp_ge_u32 s22, 44
	s_cbranch_scc1 .LBB0_57
	s_waitcnt vmcnt(0)
	s_barrier
	s_branch .Lf2_stage0

.Lfg_stage0:
	ds_read_b128 v[178:181], v130 offset:0
	ds_read_b128 v[194:197], v132 offset:16384
	ds_read_b128 v[198:201], v132 offset:18432
	ds_read_b128 v[182:185], v130 offset:2048
	ds_read_b128 v[186:189], v130 offset:4096
	ds_read_b128 v[190:193], v130 offset:6144
	ds_read_b128 v[216:219], v131 offset:0
	ds_read_b128 v[234:237], v133 offset:16384
	ds_read_b128 v[240:243], v133 offset:18432
	ds_read_b128 v[220:223], v131 offset:2048
	ds_read_b128 v[226:229], v131 offset:4096
	ds_read_b128 v[230:233], v131 offset:6144
	s_cmp_ge_u32 s13, 31
	s_cbranch_scc1 .Lfg_nl0
	s_waitcnt lgkmcnt(10)
	v_mfma_f32_32x32x16_f16 v[114:129], v[178:181], v[194:197], v[114:129]
	s_waitcnt lgkmcnt(9)
	s_add_u32 m0, s18, 0x6000
	v_mfma_f32_32x32x16_f16 v[98:113], v[178:181], v[198:201], v[98:113]
	global_load_lds_dwordx4 v139, s[14:15]
	s_waitcnt lgkmcnt(8)
	s_add_u32 m0, s18, 0x7000
	v_mfma_f32_32x32x16_f16 v[82:97], v[182:185], v[194:197], v[82:97]
	global_load_lds_dwordx4 v140, s[14:15]
	s_add_u32 m0, s18, 0x8000
	v_mfma_f32_32x32x16_f16 v[66:81], v[182:185], v[198:201], v[66:81]
	global_load_lds_dwordx4 v141, s[14:15]
	s_waitcnt lgkmcnt(7)
	s_add_u32 m0, s18, 0x9000
	v_mfma_f32_32x32x16_f16 v[50:65], v[186:189], v[194:197], v[50:65]
	global_load_lds_dwordx4 v142, s[14:15]
	s_add_u32 m0, s18, 0xa000
	v_mfma_f32_32x32x16_f16 v[34:49], v[186:189], v[198:201], v[34:49]
	global_load_lds_dwordx4 v143, s[16:17]
	s_waitcnt lgkmcnt(6)
	s_add_u32 m0, s18, 0xb000
	v_mfma_f32_32x32x16_f16 v[18:33], v[190:193], v[194:197], v[18:33]
	global_load_lds_dwordx4 v144, s[16:17]
	v_mfma_f32_32x32x16_f16 v[2:17], v[190:193], v[198:201], v[2:17]
	s_add_u32 s14, s14, 64
	s_addc_u32 s15, s15, 0
	s_add_u32 s16, s16, 64
	s_addc_u32 s17, s17, 0
	s_branch .Lfg_dd0

.Lfg_dd0:
	s_waitcnt lgkmcnt(4)
	v_mfma_f32_32x32x16_f16 v[114:129], v[216:219], v[234:237], v[114:129]
	s_waitcnt lgkmcnt(3)
	v_mfma_f32_32x32x16_f16 v[98:113], v[216:219], v[240:243], v[98:113]
	s_waitcnt lgkmcnt(2)
	v_mfma_f32_32x32x16_f16 v[82:97], v[220:223], v[234:237], v[82:97]
	v_mfma_f32_32x32x16_f16 v[66:81], v[220:223], v[240:243], v[66:81]
	s_waitcnt lgkmcnt(1)
	v_mfma_f32_32x32x16_f16 v[50:65], v[226:229], v[234:237], v[50:65]
	v_mfma_f32_32x32x16_f16 v[34:49], v[226:229], v[240:243], v[34:49]
	s_waitcnt lgkmcnt(0)
	v_mfma_f32_32x32x16_f16 v[18:33], v[230:233], v[234:237], v[18:33]
	v_mfma_f32_32x32x16_f16 v[2:17], v[230:233], v[240:243], v[2:17]
	s_add_i32 s13, s13, 1
	s_waitcnt vmcnt(0)
	s_barrier
.Lfg_stage1:
	ds_read_b128 v[178:181], v130 offset:24576
	ds_read_b128 v[194:197], v132 offset:40960
	ds_read_b128 v[198:201], v132 offset:43008
	ds_read_b128 v[182:185], v130 offset:26624
	ds_read_b128 v[186:189], v130 offset:28672
	ds_read_b128 v[190:193], v130 offset:30720
	ds_read_b128 v[216:219], v131 offset:24576
	ds_read_b128 v[234:237], v133 offset:40960
	ds_read_b128 v[240:243], v133 offset:43008
	ds_read_b128 v[220:223], v131 offset:26624
	ds_read_b128 v[226:229], v131 offset:28672
	ds_read_b128 v[230:233], v131 offset:30720
	s_cmp_ge_u32 s13, 31
	s_cbranch_scc1 .Lfg_nl1
	s_waitcnt lgkmcnt(10)
	v_mfma_f32_32x32x16_f16 v[114:129], v[178:181], v[194:197], v[114:129]
	s_waitcnt lgkmcnt(9)
	s_add_u32 m0, s18, 0x0
	v_mfma_f32_32x32x16_f16 v[98:113], v[178:181], v[198:201], v[98:113]
	global_load_lds_dwordx4 v139, s[14:15]
	s_waitcnt lgkmcnt(8)
	s_add_u32 m0, s18, 0x1000
	v_mfma_f32_32x32x16_f16 v[82:97], v[182:185], v[194:197], v[82:97]
	global_load_lds_dwordx4 v140, s[14:15]
	s_add_u32 m0, s18, 0x2000
	v_mfma_f32_32x32x16_f16 v[66:81], v[182:185], v[198:201], v[66:81]
	global_load_lds_dwordx4 v141, s[14:15]
	s_waitcnt lgkmcnt(7)
	s_add_u32 m0, s18, 0x3000
	v_mfma_f32_32x32x16_f16 v[50:65], v[186:189], v[194:197], v[50:65]
	global_load_lds_dwordx4 v142, s[14:15]
	s_add_u32 m0, s18, 0x4000
	v_mfma_f32_32x32x16_f16 v[34:49], v[186:189], v[198:201], v[34:49]
	global_load_lds_dwordx4 v143, s[16:17]
	s_waitcnt lgkmcnt(6)
	s_add_u32 m0, s18, 0x5000
	v_mfma_f32_32x32x16_f16 v[18:33], v[190:193], v[194:197], v[18:33]
	global_load_lds_dwordx4 v144, s[16:17]
	v_mfma_f32_32x32x16_f16 v[2:17], v[190:193], v[198:201], v[2:17]
	s_add_u32 s14, s14, 64
	s_addc_u32 s15, s15, 0
	s_add_u32 s16, s16, 64
	s_addc_u32 s17, s17, 0
	s_branch .Lfg_dd1

; template <class BR>
; DI void gemm_tile_w(const h16* __restrict__ A, int lda, const h16* __restrict__ B, int ldb, BR brow, int K, f32x16 (&acc)[4][2], h16* sm) {
;     ...
;   for (int kt = 0; kt < nk; kt += 2) {
;     WIDE_HALF(ra0, rb0, 0, kt)
;     WIDE_HALF(ra1, rb1, 1, kt + 1)
;   }
.Lfg_dd1:
	s_waitcnt lgkmcnt(4)
	v_mfma_f32_32x32x16_f16 v[114:129], v[216:219], v[234:237], v[114:129]
	s_waitcnt lgkmcnt(3)
	v_mfma_f32_32x32x16_f16 v[98:113], v[216:219], v[240:243], v[98:113]
	s_waitcnt lgkmcnt(2)
	v_mfma_f32_32x32x16_f16 v[82:97], v[220:223], v[234:237], v[82:97]
	v_mfma_f32_32x32x16_f16 v[66:81], v[220:223], v[240:243], v[66:81]
	s_waitcnt lgkmcnt(1)
	v_mfma_f32_32x32x16_f16 v[50:65], v[226:229], v[234:237], v[50:65]
	v_mfma_f32_32x32x16_f16 v[34:49], v[226:229], v[240:243], v[34:49]
	s_waitcnt lgkmcnt(0)
	v_mfma_f32_32x32x16_f16 v[18:33], v[230:233], v[234:237], v[18:33]
	v_mfma_f32_32x32x16_f16 v[2:17], v[230:233], v[240:243], v[2:17]
	s_add_i32 s13, s13, 1
	s_cmp_ge_u32 s13, 32
	s_cbranch_scc1 .LBB0_69
	s_waitcnt vmcnt(0)
	s_barrier
	s_branch .Lfg_stage0

.Lwo_stage0:
	ds_read_b128 v[66:69], v130 offset:0
	ds_read_b128 v[74:77], v134 offset:16384
	ds_read_b128 v[78:81], v134 offset:20480
	ds_read_b128 v[70:73], v130 offset:4096
	ds_read_b128 v[82:85], v131 offset:0
	ds_read_b128 v[90:93], v135 offset:16384
	ds_read_b128 v[94:97], v135 offset:20480
	ds_read_b128 v[86:89], v131 offset:4096
	ds_read_b128 v[98:101], v132 offset:0
	ds_read_b128 v[106:109], v136 offset:16384
	ds_read_b128 v[110:113], v136 offset:20480
	ds_read_b128 v[102:105], v132 offset:4096
	s_cmp_ge_u32 s22, 15
	s_cbranch_scc1 .Lwo_nl0
	s_waitcnt lgkmcnt(10)
	s_add_u32 m0, s38, 0x8000
	v_mfma_f32_32x32x16_f16 v[50:65], v[66:69], v[74:77], v[50:65]
	global_load_lds_dwordx4 v152, s[10:11]
	s_waitcnt lgkmcnt(9)
	s_add_u32 m0, s38, 0xc000
	v_mfma_f32_32x32x16_f16 v[34:49], v[66:69], v[78:81], v[34:49]
	global_load_lds_dwordx4 v152, s[8:9]
	s_waitcnt lgkmcnt(8)
	s_add_u32 m0, s38, 0x9000
	v_mfma_f32_32x32x16_f16 v[18:33], v[70:73], v[74:77], v[18:33]
	global_load_lds_dwordx4 v150, s[10:11]
	s_add_u32 m0, s38, 0xd000
	v_mfma_f32_32x32x16_f16 v[2:17], v[70:73], v[78:81], v[2:17]
	global_load_lds_dwordx4 v150, s[8:9]
	ds_read_b128 v[114:117], v133 offset:0
	ds_read_b128 v[122:125], v137 offset:16384
	ds_read_b128 v[126:129], v137 offset:20480
	ds_read_b128 v[118:121], v133 offset:4096
	s_waitcnt lgkmcnt(10)
	s_add_u32 m0, s38, 0xa000
	v_mfma_f32_32x32x16_f16 v[50:65], v[82:85], v[90:93], v[50:65]
	global_load_lds_dwordx4 v148, s[10:11]
	s_waitcnt lgkmcnt(9)
	s_add_u32 m0, s38, 0xe000
	v_mfma_f32_32x32x16_f16 v[34:49], v[82:85], v[94:97], v[34:49]
	global_load_lds_dwordx4 v148, s[8:9]
	s_waitcnt lgkmcnt(8)
	s_add_u32 m0, s38, 0xb000
	v_mfma_f32_32x32x16_f16 v[18:33], v[86:89], v[90:93], v[18:33]
	global_load_lds_dwordx4 v146, s[10:11]
	s_add_u32 m0, s38, 0xf000
	v_mfma_f32_32x32x16_f16 v[2:17], v[86:89], v[94:97], v[2:17]
	global_load_lds_dwordx4 v146, s[8:9]
	s_add_u32 s8, s8, 0x80
	s_addc_u32 s9, s9, 0
	s_add_u32 s10, s10, 0x80
	s_addc_u32 s11, s11, 0
	s_branch .Lwo_dd0

.Lwo_stage1:
	ds_read_b128 v[66:69], v130 offset:32768
	ds_read_b128 v[74:77], v134 offset:49152
	ds_read_b128 v[78:81], v134 offset:53248
	ds_read_b128 v[70:73], v130 offset:36864
	ds_read_b128 v[82:85], v131 offset:32768
	ds_read_b128 v[90:93], v135 offset:49152
	ds_read_b128 v[94:97], v135 offset:53248
	ds_read_b128 v[86:89], v131 offset:36864
	ds_read_b128 v[98:101], v132 offset:32768
	ds_read_b128 v[106:109], v136 offset:49152
	ds_read_b128 v[110:113], v136 offset:53248
	ds_read_b128 v[102:105], v132 offset:36864
	s_cmp_ge_u32 s22, 15
	s_cbranch_scc1 .Lwo_nl1
	s_waitcnt lgkmcnt(10)
	s_add_u32 m0, s38, 0x0
	v_mfma_f32_32x32x16_f16 v[50:65], v[66:69], v[74:77], v[50:65]
	global_load_lds_dwordx4 v152, s[10:11]
	s_waitcnt lgkmcnt(9)
	s_add_u32 m0, s38, 0x4000
	v_mfma_f32_32x32x16_f16 v[34:49], v[66:69], v[78:81], v[34:49]
	global_load_lds_dwordx4 v152, s[8:9]
	s_waitcnt lgkmcnt(8)
	s_add_u32 m0, s38, 0x1000
	v_mfma_f32_32x32x16_f16 v[18:33], v[70:73], v[74:77], v[18:33]
	global_load_lds_dwordx4 v150, s[10:11]
	s_add_u32 m0, s38, 0x5000
	v_mfma_f32_32x32x16_f16 v[2:17], v[70:73], v[78:81], v[2:17]
	global_load_lds_dwordx4 v150, s[8:9]
	ds_read_b128 v[114:117], v133 offset:32768
	ds_read_b128 v[122:125], v137 offset:49152
	ds_read_b128 v[126:129], v137 offset:53248
	ds_read_b128 v[118:121], v133 offset:36864
	s_waitcnt lgkmcnt(10)
	s_add_u32 m0, s38, 0x2000
	v_mfma_f32_32x32x16_f16 v[50:65], v[82:85], v[90:93], v[50:65]
	global_load_lds_dwordx4 v148, s[10:11]
	s_waitcnt lgkmcnt(9)
	s_add_u32 m0, s38, 0x6000
	v_mfma_f32_32x32x16_f16 v[34:49], v[82:85], v[94:97], v[34:49]
	global_load_lds_dwordx4 v148, s[8:9]
	s_waitcnt lgkmcnt(8)
	s_add_u32 m0, s38, 0x3000
	v_mfma_f32_32x32x16_f16 v[18:33], v[86:89], v[90:93], v[18:33]
	global_load_lds_dwordx4 v146, s[10:11]
	s_add_u32 m0, s38, 0x7000
	v_mfma_f32_32x32x16_f16 v[2:17], v[86:89], v[94:97], v[2:17]
	global_load_lds_dwordx4 v146, s[8:9]
	s_add_u32 s8, s8, 0x80
	s_addc_u32 s9, s9, 0
	s_add_u32 s10, s10, 0x80
	s_addc_u32 s11, s11, 0
	s_branch .Lwo_dd1

; DI void gemm_tile_deep(const h16* __restrict__ A, int lda, const h16* __restrict__ B, int ldb, int K, f32x16 (&acc)[2][2], h16* sm) {
;     ...
;   for (int kt = 0; kt < nk; kt += 2) {
;     DEEP_HALF(ra0, rb0, 0, kt)
;     DEEP_HALF(ra1, rb1, 1, kt + 1)
;   }
.Lwo_dd1:
	s_waitcnt lgkmcnt(6)
	v_mfma_f32_32x32x16_f16 v[50:65], v[98:101], v[106:109], v[50:65]
	s_waitcnt lgkmcnt(5)
	v_mfma_f32_32x32x16_f16 v[34:49], v[98:101], v[110:113], v[34:49]
	s_waitcnt lgkmcnt(4)
	v_mfma_f32_32x32x16_f16 v[18:33], v[102:105], v[106:109], v[18:33]
	v_mfma_f32_32x32x16_f16 v[2:17], v[102:105], v[110:113], v[2:17]
	s_waitcnt lgkmcnt(2)
	v_mfma_f32_32x32x16_f16 v[50:65], v[114:117], v[122:125], v[50:65]
	s_waitcnt lgkmcnt(1)
	v_mfma_f32_32x32x16_f16 v[34:49], v[114:117], v[126:129], v[34:49]
	s_waitcnt lgkmcnt(0)
	v_mfma_f32_32x32x16_f16 v[18:33], v[118:121], v[122:125], v[18:33]
	v_mfma_f32_32x32x16_f16 v[2:17], v[118:121], v[126:129], v[2:17]
	s_add_i32 s22, s22, 1
	s_cmp_ge_u32 s22, 16
	s_cbranch_scc1 .LBB0_90
	s_waitcnt vmcnt(0)
	s_barrier
	s_branch .Lwo_stage0

.Lpg_stage0:
	ds_read_b128 v[178:181], v130 offset:0
	ds_read_b128 v[194:197], v132 offset:16384
	ds_read_b128 v[198:201], v132 offset:18432
	ds_read_b128 v[182:185], v130 offset:2048
	ds_read_b128 v[186:189], v130 offset:4096
	ds_read_b128 v[190:193], v130 offset:6144
	ds_read_b128 v[216:219], v131 offset:0
	ds_read_b128 v[234:237], v133 offset:16384
	ds_read_b128 v[240:243], v133 offset:18432
	ds_read_b128 v[220:223], v131 offset:2048
	ds_read_b128 v[226:229], v131 offset:4096
	ds_read_b128 v[230:233], v131 offset:6144
	s_cmp_ge_u32 s1, 31
	s_cbranch_scc1 .Lpg_nl0
	s_waitcnt lgkmcnt(10)
	v_mfma_f32_32x32x16_f16 v[114:129], v[178:181], v[194:197], v[114:129]
	s_waitcnt lgkmcnt(9)
	s_add_u32 m0, s18, 0x6000
	v_mfma_f32_32x32x16_f16 v[98:113], v[178:181], v[198:201], v[98:113]
	global_load_lds_dwordx4 v139, s[4:5]
	s_waitcnt lgkmcnt(8)
	s_add_u32 m0, s18, 0x7000
	v_mfma_f32_32x32x16_f16 v[82:97], v[182:185], v[194:197], v[82:97]
	global_load_lds_dwordx4 v140, s[4:5]
	s_add_u32 m0, s18, 0x8000
	v_mfma_f32_32x32x16_f16 v[66:81], v[182:185], v[198:201], v[66:81]
	global_load_lds_dwordx4 v141, s[4:5]
	s_waitcnt lgkmcnt(7)
	s_add_u32 m0, s18, 0x9000
	v_mfma_f32_32x32x16_f16 v[50:65], v[186:189], v[194:197], v[50:65]
	global_load_lds_dwordx4 v142, s[4:5]
	s_add_u32 m0, s18, 0xa000
	v_mfma_f32_32x32x16_f16 v[34:49], v[186:189], v[198:201], v[34:49]
	global_load_lds_dwordx4 v143, s[6:7]
	s_waitcnt lgkmcnt(6)
	s_add_u32 m0, s18, 0xb000
	v_mfma_f32_32x32x16_f16 v[18:33], v[190:193], v[194:197], v[18:33]
	global_load_lds_dwordx4 v144, s[6:7]
	v_mfma_f32_32x32x16_f16 v[2:17], v[190:193], v[198:201], v[2:17]
	s_add_u32 s4, s4, 64
	s_addc_u32 s5, s5, 0
	s_add_u32 s6, s6, 64
	s_addc_u32 s7, s7, 0
	s_branch .Lpg_dd0

.Lpg_dd0:
	s_waitcnt lgkmcnt(4)
	v_mfma_f32_32x32x16_f16 v[114:129], v[216:219], v[234:237], v[114:129]
	s_waitcnt lgkmcnt(3)
	v_mfma_f32_32x32x16_f16 v[98:113], v[216:219], v[240:243], v[98:113]
	s_waitcnt lgkmcnt(2)
	v_mfma_f32_32x32x16_f16 v[82:97], v[220:223], v[234:237], v[82:97]
	v_mfma_f32_32x32x16_f16 v[66:81], v[220:223], v[240:243], v[66:81]
	s_waitcnt lgkmcnt(1)
	v_mfma_f32_32x32x16_f16 v[50:65], v[226:229], v[234:237], v[50:65]
	v_mfma_f32_32x32x16_f16 v[34:49], v[226:229], v[240:243], v[34:49]
	s_waitcnt lgkmcnt(0)
	v_mfma_f32_32x32x16_f16 v[18:33], v[230:233], v[234:237], v[18:33]
	v_mfma_f32_32x32x16_f16 v[2:17], v[230:233], v[240:243], v[2:17]
	s_add_i32 s1, s1, 1
	s_waitcnt vmcnt(0)
	s_barrier
.Lpg_stage1:
	ds_read_b128 v[178:181], v130 offset:24576
	ds_read_b128 v[194:197], v132 offset:40960
	ds_read_b128 v[198:201], v132 offset:43008
	ds_read_b128 v[182:185], v130 offset:26624
	ds_read_b128 v[186:189], v130 offset:28672
	ds_read_b128 v[190:193], v130 offset:30720
	ds_read_b128 v[216:219], v131 offset:24576
	ds_read_b128 v[234:237], v133 offset:40960
	ds_read_b128 v[240:243], v133 offset:43008
	ds_read_b128 v[220:223], v131 offset:26624
	ds_read_b128 v[226:229], v131 offset:28672
	ds_read_b128 v[230:233], v131 offset:30720
	s_cmp_ge_u32 s1, 31
	s_cbranch_scc1 .Lpg_nl1
	s_waitcnt lgkmcnt(10)
	v_mfma_f32_32x32x16_f16 v[114:129], v[178:181], v[194:197], v[114:129]
	s_waitcnt lgkmcnt(9)
	s_add_u32 m0, s18, 0x0
	v_mfma_f32_32x32x16_f16 v[98:113], v[178:181], v[198:201], v[98:113]
	global_load_lds_dwordx4 v139, s[4:5]
	s_waitcnt lgkmcnt(8)
	s_add_u32 m0, s18, 0x1000
	v_mfma_f32_32x32x16_f16 v[82:97], v[182:185], v[194:197], v[82:97]
	global_load_lds_dwordx4 v140, s[4:5]
	s_add_u32 m0, s18, 0x2000
	v_mfma_f32_32x32x16_f16 v[66:81], v[182:185], v[198:201], v[66:81]
	global_load_lds_dwordx4 v141, s[4:5]
	s_waitcnt lgkmcnt(7)
	s_add_u32 m0, s18, 0x3000
	v_mfma_f32_32x32x16_f16 v[50:65], v[186:189], v[194:197], v[50:65]
	global_load_lds_dwordx4 v142, s[4:5]
	s_add_u32 m0, s18, 0x4000
	v_mfma_f32_32x32x16_f16 v[34:49], v[186:189], v[198:201], v[34:49]
	global_load_lds_dwordx4 v143, s[6:7]
	s_waitcnt lgkmcnt(6)
	s_add_u32 m0, s18, 0x5000
	v_mfma_f32_32x32x16_f16 v[18:33], v[190:193], v[194:197], v[18:33]
	global_load_lds_dwordx4 v144, s[6:7]
	v_mfma_f32_32x32x16_f16 v[2:17], v[190:193], v[198:201], v[2:17]
	s_add_u32 s4, s4, 64
	s_addc_u32 s5, s5, 0
	s_add_u32 s6, s6, 64
	s_addc_u32 s7, s7, 0
	s_branch .Lpg_dd1

; template <class BR>
; DI void gemm_tile_w(const h16* __restrict__ A, int lda, const h16* __restrict__ B, int ldb, BR brow, int K, f32x16 (&acc)[4][2], h16* sm) {
;     ...
;   for (int kt = 0; kt < nk; kt += 2) {
;     WIDE_HALF(ra0, rb0, 0, kt)
;     WIDE_HALF(ra1, rb1, 1, kt + 1)
;   }
.Lpg_dd1:
	s_waitcnt lgkmcnt(4)
	v_mfma_f32_32x32x16_f16 v[114:129], v[216:219], v[234:237], v[114:129]
	s_waitcnt lgkmcnt(3)
	v_mfma_f32_32x32x16_f16 v[98:113], v[216:219], v[240:243], v[98:113]
	s_waitcnt lgkmcnt(2)
	v_mfma_f32_32x32x16_f16 v[82:97], v[220:223], v[234:237], v[82:97]
	v_mfma_f32_32x32x16_f16 v[66:81], v[220:223], v[240:243], v[66:81]
	s_waitcnt lgkmcnt(1)
	v_mfma_f32_32x32x16_f16 v[50:65], v[226:229], v[234:237], v[50:65]
	v_mfma_f32_32x32x16_f16 v[34:49], v[226:229], v[240:243], v[34:49]
	s_waitcnt lgkmcnt(0)
	v_mfma_f32_32x32x16_f16 v[18:33], v[230:233], v[234:237], v[18:33]
	v_mfma_f32_32x32x16_f16 v[2:17], v[230:233], v[240:243], v[2:17]
	s_add_i32 s1, s1, 1
	s_cmp_ge_u32 s1, 32
	s_cbranch_scc1 .LBB0_700
	s_waitcnt vmcnt(0)
	s_barrier
	s_branch .Lpg_stage0
